# diff-attention finalize: 16 per-row sub-LN sum butterflies (5 ds_bpermute round trips each) by DPP adds + permlane16 swap, bit-identical pairing
# baseline (speedup 1.0000x reference)
; __device__ __forceinline__ unsigned cvtpk(float lo, float hi) { unsigned r; asm volatile("v_cvt_pk_bf16_f32 %0, %1, %2" : "=v"(r) : "v"(lo), "v"(hi)); return r; }
; __device__ __forceinline__ float sx(float v, int mask, int lane) { return __int_as_float(__builtin_amdgcn_ds_bpermute((lane ^ mask) << 2, __float_as_int(v))); }
; __device__ __forceinline__ int crow(int r, int hi) { return (r & 3) + 8 * (r >> 2) + 4 * hi; }
;     __device__ __forceinline__ long qtok(int wid, int i) const { return (long)b * T + res + dil * (qs0 + 32 * wid + i); }
;     __device__ __forceinline__ long qtok(int wid, int i) const { return (long)b * T + 256 * qb + 32 * wid + i; }
;     __device__ __forceinline__ long qtok(int wid, int i) const { return (long)b * T + 128 * qb + 32 * (wid & 3) + i; }
; template <class Pol>
; __device__ __forceinline__ void attn_unit(const Pol& P, LAS unsigned char* lds, const Ptrs& X, bf16x8& pq0, bf16x8& pq1, bf16x8& pq2, bf16x8& pq3, bf16x8& pk_, bf16x8& pv_, bool have, const Pol& Pn, bool hasn) {
;     ...
;         if (wid < 4) {
; #pragma unroll
;             for (int r = 0; r < 16; ++r) { const int row = 32 * wid + crow(r, hi); float s = 0.f;
; #pragma unroll
;                 for (int d = 0; d < NB; ++d) { const float y = o[d][r] * rli[r] - XB[row * 128 + d * 32 + r32]; o[d][r] = y; s += y * y; }
;                 s += sx(s, 1, lane); s += sx(s, 2, lane); s += sx(s, 4, lane); s += sx(s, 8, lane); s += sx(s, 16, lane);
;                 const float rs = (1.0f - LAM_INIT) / sqrtf(s * (1.0f / 128.f) + SUBLN_EPS);
;                 const long tok = P.qtok(wid, crow(r, hi));
; #pragma unroll
;                 for (int d = 0; d < NB; ++d) X.att[tok * D + P.h * 128 + d * 32 + r32] = (bf16_t)(cvtpk(o[d][r] * rs * X.subln[d * 32 + r32], 0.f) & 0xffffu); }
;         }
.LBB0_297:
	s_cmp_gt_i32 s2, 3
	v_mov_b64_e32 v[242:243], v[218:219]
	s_waitcnt lgkmcnt(0)
	s_barrier
	s_cbranch_scc1 .LBB0_299
	s_lshl_b32 s0, s2, 14
	s_add_i32 s0, s0, 0
	s_add_i32 s0, s0, 0x11000
	v_lshlrev_b32_e32 v4, 2, v204
	v_add_u32_e32 v11, s0, v4
	v_lshlrev_b32_e32 v2, 2, v230
	v_lshl_add_u32 v154, v229, 11, v11
	v_xor_b32_e32 v10, 4, v2
	v_xor_b32_e32 v9, 8, v2
	v_xor_b32_e32 v8, 16, v2
	v_xor_b32_e32 v7, 32, v2
	v_xor_b32_e32 v6, 64, v2
	ds_read2_b32 v[2:3], v154 offset1:32
	v_mov_b32_e32 v157, 0x3727c5ac
	s_mov_b32 s2, 0xf800000
	s_mov_b32 s3, 0x3f24fd5c
	v_readlane_b32 s6, v254, 27
	s_waitcnt lgkmcnt(0)
	v_fma_f32 v155, v112, v0, -v2
	v_fma_f32 v128, v128, v0, -v3
	ds_read2_b32 v[2:3], v154 offset0:64 offset1:96
	v_mul_f32_e32 v112, v128, v128
	v_fmac_f32_e32 v112, v155, v155
	v_readlane_b32 s7, v254, 28
	s_nop 4
	global_load_dword v206, v4, s[6:7]
	global_load_dword v207, v4, s[6:7] offset:128
	global_load_dword v208, v4, s[6:7] offset:256
	global_load_dword v209, v4, s[6:7] offset:384
	s_lshl_b32 s26, s40, 1
	s_waitcnt lgkmcnt(0)
	v_fma_f32 v96, v96, v0, -v2
	v_fmac_f32_e32 v112, v96, v96
	v_fma_f32 v80, v80, v0, -v3
	v_fmac_f32_e32 v112, v80, v80
	s_nop 1
	v_add_f32_dpp v0, v112, v112 quad_perm:[1,0,3,2] row_mask:0xf bank_mask:0xf
	s_nop 1
	v_add_f32_dpp v0, v0, v0 quad_perm:[2,3,0,1] row_mask:0xf bank_mask:0xf
	s_nop 1
	v_add_f32_dpp v0, v0, v0 row_half_mirror row_mask:0xf bank_mask:0xf
	s_nop 1
	v_add_f32_dpp v0, v0, v0 row_mirror row_mask:0xf bank_mask:0xf
	v_mov_b32_e32 v2, v0
	s_nop 1
	v_permlane16_swap_b32_e32 v2, v0
	v_add_f32_e32 v0, v0, v2
	v_fmamk_f32 v0, v0, 0x3c000000, v157
	v_cmp_gt_f32_e32 vcc, s2, v0
	v_mul_f32_e32 v2, 0x4f800000, v0
	s_nop 0
	v_cndmask_b32_e32 v0, v0, v2, vcc
	v_sqrt_f32_e32 v2, v0
	s_nop 0
	v_add_u32_e32 v3, -1, v2
	v_fma_f32 v112, -v3, v2, v0
	v_cmp_ge_f32_e64 s[4:5], 0, v112
	v_add_u32_e32 v112, 1, v2
	s_nop 0
	v_cndmask_b32_e64 v3, v2, v3, s[4:5]
	v_fma_f32 v2, -v112, v2, v0
	v_cmp_lt_f32_e64 s[4:5], 0, v2
	s_nop 1
	v_cndmask_b32_e64 v2, v3, v112, s[4:5]
	v_mul_f32_e32 v3, 0x37800000, v2
	v_cndmask_b32_e32 v2, v2, v3, vcc
	v_cmp_class_f32_e32 vcc, v0, v216
	s_nop 1
	v_cndmask_b32_e32 v0, v2, v0, vcc
	v_div_scale_f32 v2, s[0:1], v0, v0, s3
	v_rcp_f32_e32 v3, v2
	s_nop 0
	v_fma_f32 v112, -v2, v3, 1.0
	v_fmac_f32_e32 v3, v112, v3
	v_div_scale_f32 v112, vcc, s3, v0, s3
	v_mul_f32_e32 v154, v112, v3
	v_fma_f32 v156, -v2, v154, v112
	v_fmac_f32_e32 v154, v156, v3
	v_fma_f32 v2, -v2, v154, v112
	v_div_fmas_f32 v2, v2, v3, v154
	s_waitcnt vmcnt(0)
	v_mov_b32_e32 v154, v206
	v_div_fixup_f32 v112, v2, v0, s3
	v_or_b32_e32 v0, s20, v228
	v_or_b32_e32 v0, s31, v0
	v_lshlrev_b64 v[2:3], 11, v[0:1]
	v_mul_f32_e32 v0, v155, v112
	v_lshl_add_u64 v[2:3], s[90:91], 0, v[2:3]
	v_lshl_add_u64 v[2:3], v[2:3], 0, s[26:27]
	v_mul_f32_e32 v128, v128, v112
	v_mul_f32_e32 v96, v96, v112
	v_mul_f32_e32 v80, v80, v112
	v_or_b32_e32 v112, 1, v228
	s_nop 0
	v_mul_f32_e32 v0, v154, v0
	v_cvt_pk_bf16_f32 v154, v0, v1
	v_lshlrev_b32_e32 v0, 1, v204
	v_lshl_add_u64 v[2:3], v[2:3], 0, v[0:1]
	global_store_short v[2:3], v154, off
	v_mov_b32_e32 v154, v207
	s_nop 0
	v_mul_f32_e32 v128, v154, v128
	v_cvt_pk_bf16_f32 v128, v128, v1
	global_store_short v[2:3], v128, off offset:64
	v_mov_b32_e32 v128, v208
	s_nop 0
	v_mul_f32_e32 v96, v128, v96
	v_cvt_pk_bf16_f32 v96, v96, v1
	global_store_short v[2:3], v96, off offset:128
	v_mov_b32_e32 v96, v209
	s_nop 0
	v_mul_f32_e32 v80, v80, v96
	v_cvt_pk_bf16_f32 v80, v80, v1
	global_store_short v[2:3], v80, off offset:192
	v_lshl_add_u32 v80, v112, 9, v11
	ds_read2_b32 v[2:3], v80 offset1:32
	s_waitcnt lgkmcnt(0)
	v_fma_f32 v113, v113, v153, -v2
	v_fma_f32 v128, v129, v153, -v3
	ds_read2_b32 v[2:3], v80 offset0:64 offset1:96
	v_mul_f32_e32 v129, v128, v128
	v_fmac_f32_e32 v129, v113, v113
	s_waitcnt lgkmcnt(0)
	v_fma_f32 v96, v97, v153, -v2
	v_fmac_f32_e32 v129, v96, v96
	v_fma_f32 v80, v81, v153, -v3
	v_fmac_f32_e32 v129, v80, v80
	s_nop 1
	v_add_f32_dpp v2, v129, v129 quad_perm:[1,0,3,2] row_mask:0xf bank_mask:0xf
	s_nop 1
	v_add_f32_dpp v2, v2, v2 quad_perm:[2,3,0,1] row_mask:0xf bank_mask:0xf
	s_nop 1
	v_add_f32_dpp v2, v2, v2 row_half_mirror row_mask:0xf bank_mask:0xf
	s_nop 1
	v_add_f32_dpp v2, v2, v2 row_mirror row_mask:0xf bank_mask:0xf
	v_mov_b32_e32 v3, v2
	s_nop 1
	v_permlane16_swap_b32_e32 v3, v2
	v_add_f32_e32 v2, v2, v3
	v_fmamk_f32 v2, v2, 0x3c000000, v157
	v_cmp_gt_f32_e32 vcc, s2, v2
	v_mul_f32_e32 v3, 0x4f800000, v2
	s_nop 0
	v_cndmask_b32_e32 v2, v2, v3, vcc
	v_sqrt_f32_e32 v3, v2
	s_nop 0
	v_add_u32_e32 v81, -1, v3
	v_fma_f32 v97, -v81, v3, v2
	v_cmp_ge_f32_e64 s[4:5], 0, v97
	v_add_u32_e32 v97, 1, v3
	s_nop 0
	v_cndmask_b32_e64 v81, v3, v81, s[4:5]
	v_fma_f32 v3, -v97, v3, v2
	v_cmp_lt_f32_e64 s[4:5], 0, v3
	s_nop 1
	v_cndmask_b32_e64 v3, v81, v97, s[4:5]
	v_mul_f32_e32 v81, 0x37800000, v3
	v_cndmask_b32_e32 v3, v3, v81, vcc
	v_cmp_class_f32_e32 vcc, v2, v216
	s_nop 1
	v_cndmask_b32_e32 v2, v3, v2, vcc
	v_div_scale_f32 v3, s[0:1], v2, v2, s3
	v_rcp_f32_e32 v81, v3
	s_nop 0
	v_fma_f32 v97, -v3, v81, 1.0
	v_fmac_f32_e32 v81, v97, v81
	v_div_scale_f32 v97, vcc, s3, v2, s3
	v_mul_f32_e32 v129, v97, v81
	v_fma_f32 v153, -v3, v129, v97
	v_fmac_f32_e32 v129, v153, v81
	v_fma_f32 v3, -v3, v129, v97
	v_div_fmas_f32 v3, v3, v81, v129
	v_div_fixup_f32 v81, v3, v2, s3
	v_or_b32_e32 v2, s20, v112
	v_mov_b32_e32 v112, v206
	v_mul_f32_e32 v97, v113, v81
	v_or_b32_e32 v2, s31, v2
	v_mov_b32_e32 v3, v1
	v_lshlrev_b64 v[2:3], 11, v[2:3]
	v_lshl_add_u64 v[2:3], s[90:91], 0, v[2:3]
	v_lshl_add_u64 v[2:3], v[2:3], 0, s[26:27]
	v_lshl_add_u64 v[2:3], v[2:3], 0, v[0:1]
	v_mul_f32_e32 v96, v96, v81
	v_mul_f32_e32 v80, v80, v81
	s_nop 0
	v_mul_f32_e32 v97, v112, v97
	v_cvt_pk_bf16_f32 v97, v97, v1
	v_mov_b32_e32 v112, v207
	s_nop 0
	global_store_short v[2:3], v97, off
	v_mul_f32_e32 v97, v128, v81
	s_nop 0
	v_mul_f32_e32 v97, v112, v97
	v_cvt_pk_bf16_f32 v97, v97, v1
	global_store_short v[2:3], v97, off offset:64
	v_mov_b32_e32 v97, v208
	s_nop 0
	v_mul_f32_e32 v96, v97, v96
	v_cvt_pk_bf16_f32 v96, v96, v1
	v_mov_b32_e32 v81, v209
	s_nop 0
	v_mul_f32_e32 v80, v80, v81
	global_store_short v[2:3], v96, off offset:128
	v_cvt_pk_bf16_f32 v80, v80, v1
	v_or_b32_e32 v96, 2, v228
	global_store_short v[2:3], v80, off offset:192
	v_lshl_add_u32 v80, v96, 9, v11
	ds_read2_b32 v[2:3], v80 offset1:32
	s_waitcnt lgkmcnt(0)
; __device__ __forceinline__ unsigned cvtpk(float lo, float hi) { unsigned r; asm volatile("v_cvt_pk_bf16_f32 %0, %1, %2" : "=v"(r) : "v"(lo), "v"(hi)); return r; }
; __device__ __forceinline__ float sx(float v, int mask, int lane) { return __int_as_float(__builtin_amdgcn_ds_bpermute((lane ^ mask) << 2, __float_as_int(v))); }
; __device__ __forceinline__ int crow(int r, int hi) { return (r & 3) + 8 * (r >> 2) + 4 * hi; }
;     __device__ __forceinline__ long qtok(int wid, int i) const { return (long)b * T + res + dil * (qs0 + 32 * wid + i); }
;     __device__ __forceinline__ long qtok(int wid, int i) const { return (long)b * T + 256 * qb + 32 * wid + i; }
;     __device__ __forceinline__ long qtok(int wid, int i) const { return (long)b * T + 128 * qb + 32 * (wid & 3) + i; }
; template <class Pol>
; __device__ __forceinline__ void attn_unit(const Pol& P, LAS unsigned char* lds, const Ptrs& X, bf16x8& pq0, bf16x8& pq1, bf16x8& pq2, bf16x8& pq3, bf16x8& pk_, bf16x8& pv_, bool have, const Pol& Pn, bool hasn) {
;     ...
;         if (wid < 4) {
; #pragma unroll
;             for (int r = 0; r < 16; ++r) { const int row = 32 * wid + crow(r, hi); float s = 0.f;
; #pragma unroll
;                 for (int d = 0; d < NB; ++d) { const float y = o[d][r] * rli[r] - XB[row * 128 + d * 32 + r32]; o[d][r] = y; s += y * y; }
;                 s += sx(s, 1, lane); s += sx(s, 2, lane); s += sx(s, 4, lane); s += sx(s, 8, lane); s += sx(s, 16, lane);
;                 const float rs = (1.0f - LAM_INIT) / sqrtf(s * (1.0f / 128.f) + SUBLN_EPS);
;                 const long tok = P.qtok(wid, crow(r, hi));
; #pragma unroll
;                 for (int d = 0; d < NB; ++d) X.att[tok * D + P.h * 128 + d * 32 + r32] = (bf16_t)(cvtpk(o[d][r] * rs * X.subln[d * 32 + r32], 0.f) & 0xffffu); }
;         }
	v_fma_f32 v97, v114, v152, -v2
	v_fma_f32 v112, v130, v152, -v3
	ds_read2_b32 v[2:3], v80 offset0:64 offset1:96
	v_mul_f32_e32 v113, v112, v112
	v_fmac_f32_e32 v113, v97, v97
	s_waitcnt lgkmcnt(0)
	v_fma_f32 v81, v98, v152, -v2
	v_fmac_f32_e32 v113, v81, v81
	v_fma_f32 v80, v82, v152, -v3
	v_fmac_f32_e32 v113, v80, v80
	s_nop 1
	v_add_f32_dpp v2, v113, v113 quad_perm:[1,0,3,2] row_mask:0xf bank_mask:0xf
	s_nop 1
	v_add_f32_dpp v2, v2, v2 quad_perm:[2,3,0,1] row_mask:0xf bank_mask:0xf
	s_nop 1
	v_add_f32_dpp v2, v2, v2 row_half_mirror row_mask:0xf bank_mask:0xf
	s_nop 1
	v_add_f32_dpp v2, v2, v2 row_mirror row_mask:0xf bank_mask:0xf
	v_mov_b32_e32 v3, v2
	s_nop 1
	v_permlane16_swap_b32_e32 v3, v2
	v_add_f32_e32 v2, v2, v3
	v_fmamk_f32 v2, v2, 0x3c000000, v157
	v_cmp_gt_f32_e32 vcc, s2, v2
	v_mul_f32_e32 v3, 0x4f800000, v2
	s_nop 0
	v_cndmask_b32_e32 v2, v2, v3, vcc
	v_sqrt_f32_e32 v3, v2
	s_nop 0
	v_add_u32_e32 v82, -1, v3
	v_fma_f32 v98, -v82, v3, v2
	v_cmp_ge_f32_e64 s[4:5], 0, v98
	v_add_u32_e32 v98, 1, v3
	s_nop 0
	v_cndmask_b32_e64 v82, v3, v82, s[4:5]
	v_fma_f32 v3, -v98, v3, v2
	v_cmp_lt_f32_e64 s[4:5], 0, v3
	s_nop 1
	v_cndmask_b32_e64 v3, v82, v98, s[4:5]
	v_mul_f32_e32 v82, 0x37800000, v3
	v_cndmask_b32_e32 v3, v3, v82, vcc
	v_cmp_class_f32_e32 vcc, v2, v216
	s_nop 1
	v_cndmask_b32_e32 v2, v3, v2, vcc
	v_div_scale_f32 v3, s[0:1], v2, v2, s3
	v_rcp_f32_e32 v82, v3
	s_nop 0
	v_fma_f32 v98, -v3, v82, 1.0
	v_fmac_f32_e32 v82, v98, v82
	v_div_scale_f32 v98, vcc, s3, v2, s3
	v_mul_f32_e32 v113, v98, v82
	v_fma_f32 v114, -v3, v113, v98
	v_fmac_f32_e32 v113, v114, v82
	v_fma_f32 v3, -v3, v113, v98
	v_div_fmas_f32 v3, v3, v82, v113
	v_div_fixup_f32 v82, v3, v2, s3
	v_or_b32_e32 v2, s20, v96
	v_mul_f32_e32 v96, v97, v82
	v_mov_b32_e32 v97, v206
	v_or_b32_e32 v2, s31, v2
	v_mov_b32_e32 v3, v1
	v_lshlrev_b64 v[2:3], 11, v[2:3]
	v_lshl_add_u64 v[2:3], s[90:91], 0, v[2:3]
	v_lshl_add_u64 v[2:3], v[2:3], 0, s[26:27]
	v_lshl_add_u64 v[2:3], v[2:3], 0, v[0:1]
	v_mul_f32_e32 v81, v81, v82
	v_mul_f32_e32 v80, v80, v82
	s_nop 0
	v_mul_f32_e32 v96, v97, v96
	v_cvt_pk_bf16_f32 v96, v96, v1
	v_mov_b32_e32 v97, v207
	s_nop 0
	global_store_short v[2:3], v96, off
	v_mul_f32_e32 v96, v112, v82
	s_nop 0
	v_mul_f32_e32 v96, v97, v96
	v_cvt_pk_bf16_f32 v96, v96, v1
	global_store_short v[2:3], v96, off offset:64
	v_mov_b32_e32 v96, v208
	s_nop 0
	v_mul_f32_e32 v81, v96, v81
	v_cvt_pk_bf16_f32 v81, v81, v1
	global_store_short v[2:3], v81, off offset:128
	v_mov_b32_e32 v81, v209
	v_or_b32_e32 v96, 3, v228
	s_nop 0
	v_mul_f32_e32 v80, v80, v81
	v_cvt_pk_bf16_f32 v80, v80, v1
	global_store_short v[2:3], v80, off offset:192
	v_lshl_add_u32 v80, v96, 9, v11
	ds_read2_b32 v[2:3], v80 offset1:32
	s_waitcnt lgkmcnt(0)
	v_fma_f32 v97, v115, v151, -v2
	v_fma_f32 v98, v131, v151, -v3
	ds_read2_b32 v[2:3], v80 offset0:64 offset1:96
	v_mul_f32_e32 v82, v98, v98
	v_fmac_f32_e32 v82, v97, v97
	s_waitcnt lgkmcnt(0)
	v_fma_f32 v81, v99, v151, -v2
	v_fmac_f32_e32 v82, v81, v81
	v_fma_f32 v80, v83, v151, -v3
	v_fmac_f32_e32 v82, v80, v80
	s_nop 1
	v_add_f32_dpp v2, v82, v82 quad_perm:[1,0,3,2] row_mask:0xf bank_mask:0xf
	s_nop 1
	v_add_f32_dpp v2, v2, v2 quad_perm:[2,3,0,1] row_mask:0xf bank_mask:0xf
	s_nop 1
	v_add_f32_dpp v2, v2, v2 row_half_mirror row_mask:0xf bank_mask:0xf
	s_nop 1
	v_add_f32_dpp v2, v2, v2 row_mirror row_mask:0xf bank_mask:0xf
	v_mov_b32_e32 v3, v2
	s_nop 1
	v_permlane16_swap_b32_e32 v3, v2
	v_add_f32_e32 v2, v2, v3
	v_fmamk_f32 v2, v2, 0x3c000000, v157
	v_cmp_gt_f32_e32 vcc, s2, v2
	v_mul_f32_e32 v3, 0x4f800000, v2
	s_nop 0
	v_cndmask_b32_e32 v2, v2, v3, vcc
	v_sqrt_f32_e32 v3, v2
	s_nop 0
	v_add_u32_e32 v82, -1, v3
	v_fma_f32 v83, -v82, v3, v2
	v_cmp_ge_f32_e64 s[4:5], 0, v83
	v_add_u32_e32 v83, 1, v3
	s_nop 0
	v_cndmask_b32_e64 v82, v3, v82, s[4:5]
	v_fma_f32 v3, -v83, v3, v2
	v_cmp_lt_f32_e64 s[4:5], 0, v3
	s_nop 1
	v_cndmask_b32_e64 v3, v82, v83, s[4:5]
	v_mul_f32_e32 v82, 0x37800000, v3
	v_cndmask_b32_e32 v3, v3, v82, vcc
	v_cmp_class_f32_e32 vcc, v2, v216
	s_nop 1
	v_cndmask_b32_e32 v2, v3, v2, vcc
	v_div_scale_f32 v3, s[0:1], v2, v2, s3
	v_rcp_f32_e32 v82, v3
	s_nop 0
	v_fma_f32 v83, -v3, v82, 1.0
	v_fmac_f32_e32 v82, v83, v82
	v_div_scale_f32 v83, vcc, s3, v2, s3
	v_mul_f32_e32 v99, v83, v82
	v_fma_f32 v112, -v3, v99, v83
	v_fmac_f32_e32 v99, v112, v82
	v_fma_f32 v3, -v3, v99, v83
	v_div_fmas_f32 v3, v3, v82, v99
	v_div_fixup_f32 v82, v3, v2, s3
	v_or_b32_e32 v2, s20, v96
	v_mov_b32_e32 v96, v206
	v_mul_f32_e32 v83, v97, v82
	v_or_b32_e32 v2, s31, v2
	v_mov_b32_e32 v3, v1
	v_lshlrev_b64 v[2:3], 11, v[2:3]
	v_lshl_add_u64 v[2:3], s[90:91], 0, v[2:3]
	v_lshl_add_u64 v[2:3], v[2:3], 0, s[26:27]
	v_lshl_add_u64 v[2:3], v[2:3], 0, v[0:1]
	v_mul_f32_e32 v81, v81, v82
	v_mul_f32_e32 v80, v80, v82
	s_nop 0
	v_mul_f32_e32 v83, v96, v83
	v_cvt_pk_bf16_f32 v83, v83, v1
	v_mov_b32_e32 v96, v207
	s_nop 0
	global_store_short v[2:3], v83, off
	v_mul_f32_e32 v83, v98, v82
	s_nop 0
	v_mul_f32_e32 v83, v96, v83
	v_cvt_pk_bf16_f32 v83, v83, v1
	global_store_short v[2:3], v83, off offset:64
	v_mov_b32_e32 v83, v208
	s_nop 0
	v_mul_f32_e32 v81, v83, v81
	v_cvt_pk_bf16_f32 v81, v81, v1
	global_store_short v[2:3], v81, off offset:128
	v_mov_b32_e32 v81, v209
	v_or_b32_e32 v83, 8, v228
	s_nop 0
	v_mul_f32_e32 v80, v80, v81
	v_cvt_pk_bf16_f32 v80, v80, v1
	global_store_short v[2:3], v80, off offset:192
	v_lshl_add_u32 v80, v83, 9, v11
	ds_read2_b32 v[2:3], v80 offset1:32
	s_waitcnt lgkmcnt(0)
	v_fma_f32 v96, v116, v150, -v2
	v_fma_f32 v97, v132, v150, -v3
	ds_read2_b32 v[2:3], v80 offset0:64 offset1:96
	v_mul_f32_e32 v82, v97, v97
	v_fmac_f32_e32 v82, v96, v96
	s_waitcnt lgkmcnt(0)
; __device__ __forceinline__ unsigned cvtpk(float lo, float hi) { unsigned r; asm volatile("v_cvt_pk_bf16_f32 %0, %1, %2" : "=v"(r) : "v"(lo), "v"(hi)); return r; }
; __device__ __forceinline__ float sx(float v, int mask, int lane) { return __int_as_float(__builtin_amdgcn_ds_bpermute((lane ^ mask) << 2, __float_as_int(v))); }
; __device__ __forceinline__ int crow(int r, int hi) { return (r & 3) + 8 * (r >> 2) + 4 * hi; }
;     __device__ __forceinline__ long qtok(int wid, int i) const { return (long)b * T + res + dil * (qs0 + 32 * wid + i); }
;     __device__ __forceinline__ long qtok(int wid, int i) const { return (long)b * T + 256 * qb + 32 * wid + i; }
;     __device__ __forceinline__ long qtok(int wid, int i) const { return (long)b * T + 128 * qb + 32 * (wid & 3) + i; }
; template <class Pol>
; __device__ __forceinline__ void attn_unit(const Pol& P, LAS unsigned char* lds, const Ptrs& X, bf16x8& pq0, bf16x8& pq1, bf16x8& pq2, bf16x8& pq3, bf16x8& pk_, bf16x8& pv_, bool have, const Pol& Pn, bool hasn) {
;     ...
;         if (wid < 4) {
; #pragma unroll
;             for (int r = 0; r < 16; ++r) { const int row = 32 * wid + crow(r, hi); float s = 0.f;
; #pragma unroll
;                 for (int d = 0; d < NB; ++d) { const float y = o[d][r] * rli[r] - XB[row * 128 + d * 32 + r32]; o[d][r] = y; s += y * y; }
;                 s += sx(s, 1, lane); s += sx(s, 2, lane); s += sx(s, 4, lane); s += sx(s, 8, lane); s += sx(s, 16, lane);
;                 const float rs = (1.0f - LAM_INIT) / sqrtf(s * (1.0f / 128.f) + SUBLN_EPS);
;                 const long tok = P.qtok(wid, crow(r, hi));
; #pragma unroll
;                 for (int d = 0; d < NB; ++d) X.att[tok * D + P.h * 128 + d * 32 + r32] = (bf16_t)(cvtpk(o[d][r] * rs * X.subln[d * 32 + r32], 0.f) & 0xffffu); }
;         }
	v_fma_f32 v81, v100, v150, -v2
	v_fmac_f32_e32 v82, v81, v81
	v_fma_f32 v80, v84, v150, -v3
	v_fmac_f32_e32 v82, v80, v80
	s_nop 1
	v_add_f32_dpp v2, v82, v82 quad_perm:[1,0,3,2] row_mask:0xf bank_mask:0xf
	s_nop 1
	v_add_f32_dpp v2, v2, v2 quad_perm:[2,3,0,1] row_mask:0xf bank_mask:0xf
	s_nop 1
	v_add_f32_dpp v2, v2, v2 row_half_mirror row_mask:0xf bank_mask:0xf
	s_nop 1
	v_add_f32_dpp v2, v2, v2 row_mirror row_mask:0xf bank_mask:0xf
	v_mov_b32_e32 v3, v2
	s_nop 1
	v_permlane16_swap_b32_e32 v3, v2
	v_add_f32_e32 v2, v2, v3
	v_fmamk_f32 v2, v2, 0x3c000000, v157
	v_cmp_gt_f32_e32 vcc, s2, v2
	v_mul_f32_e32 v3, 0x4f800000, v2
	s_nop 0
	v_cndmask_b32_e32 v2, v2, v3, vcc
	v_sqrt_f32_e32 v3, v2
	s_nop 0
	v_add_u32_e32 v82, -1, v3
	v_fma_f32 v84, -v82, v3, v2
	v_cmp_ge_f32_e64 s[4:5], 0, v84
	v_add_u32_e32 v84, 1, v3
	s_nop 0
	v_cndmask_b32_e64 v82, v3, v82, s[4:5]
	v_fma_f32 v3, -v84, v3, v2
	v_cmp_lt_f32_e64 s[4:5], 0, v3
	s_nop 1
	v_cndmask_b32_e64 v3, v82, v84, s[4:5]
	v_mul_f32_e32 v82, 0x37800000, v3
	v_cndmask_b32_e32 v3, v3, v82, vcc
	v_cmp_class_f32_e32 vcc, v2, v216
	s_nop 1
	v_cndmask_b32_e32 v2, v3, v2, vcc
	v_div_scale_f32 v3, s[0:1], v2, v2, s3
	v_rcp_f32_e32 v82, v3
	s_nop 0
	v_fma_f32 v84, -v3, v82, 1.0
	v_fmac_f32_e32 v82, v84, v82
	v_div_scale_f32 v84, vcc, s3, v2, s3
	v_mul_f32_e32 v98, v84, v82
	v_fma_f32 v99, -v3, v98, v84
	v_fmac_f32_e32 v98, v99, v82
	v_fma_f32 v3, -v3, v98, v84
	v_mov_b32_e32 v84, v206
	v_div_fmas_f32 v3, v3, v82, v98
	v_div_fixup_f32 v82, v3, v2, s3
	v_or_b32_e32 v2, s20, v83
	v_mul_f32_e32 v83, v96, v82
	v_or_b32_e32 v2, s31, v2
	v_mov_b32_e32 v3, v1
	v_lshlrev_b64 v[2:3], 11, v[2:3]
	v_lshl_add_u64 v[2:3], s[90:91], 0, v[2:3]
	v_lshl_add_u64 v[2:3], v[2:3], 0, s[26:27]
	v_lshl_add_u64 v[2:3], v[2:3], 0, v[0:1]
	v_mul_f32_e32 v81, v81, v82
	v_mul_f32_e32 v80, v80, v82
	s_nop 0
	v_mul_f32_e32 v83, v84, v83
	v_cvt_pk_bf16_f32 v83, v83, v1
	v_mov_b32_e32 v84, v207
	s_nop 0
	global_store_short v[2:3], v83, off
	v_mul_f32_e32 v83, v97, v82
	s_nop 0
	v_mul_f32_e32 v83, v84, v83
	v_cvt_pk_bf16_f32 v83, v83, v1
	global_store_short v[2:3], v83, off offset:64
	v_mov_b32_e32 v83, v208
	s_nop 0
	v_mul_f32_e32 v81, v83, v81
	v_cvt_pk_bf16_f32 v81, v81, v1
	global_store_short v[2:3], v81, off offset:128
	v_mov_b32_e32 v81, v209
	v_or_b32_e32 v83, 9, v228
	s_nop 0
	v_mul_f32_e32 v80, v80, v81
	v_cvt_pk_bf16_f32 v80, v80, v1
	global_store_short v[2:3], v80, off offset:192
	v_lshl_add_u32 v80, v83, 9, v11
	ds_read2_b32 v[2:3], v80 offset1:32
	s_waitcnt lgkmcnt(0)
	v_fma_f32 v84, v117, v149, -v2
	v_fma_f32 v96, v133, v149, -v3
	ds_read2_b32 v[2:3], v80 offset0:64 offset1:96
	v_mul_f32_e32 v82, v96, v96
	v_fmac_f32_e32 v82, v84, v84
	s_waitcnt lgkmcnt(0)
	v_fma_f32 v81, v101, v149, -v2
	v_fmac_f32_e32 v82, v81, v81
	v_fma_f32 v80, v85, v149, -v3
	v_fmac_f32_e32 v82, v80, v80
	s_nop 1
	v_add_f32_dpp v2, v82, v82 quad_perm:[1,0,3,2] row_mask:0xf bank_mask:0xf
	s_nop 1
	v_add_f32_dpp v2, v2, v2 quad_perm:[2,3,0,1] row_mask:0xf bank_mask:0xf
	s_nop 1
	v_add_f32_dpp v2, v2, v2 row_half_mirror row_mask:0xf bank_mask:0xf
	s_nop 1
	v_add_f32_dpp v2, v2, v2 row_mirror row_mask:0xf bank_mask:0xf
	v_mov_b32_e32 v3, v2
	s_nop 1
	v_permlane16_swap_b32_e32 v3, v2
	v_add_f32_e32 v2, v2, v3
	v_fmamk_f32 v2, v2, 0x3c000000, v157
	v_cmp_gt_f32_e32 vcc, s2, v2
	v_mul_f32_e32 v3, 0x4f800000, v2
	s_nop 0
	v_cndmask_b32_e32 v2, v2, v3, vcc
	v_sqrt_f32_e32 v3, v2
	s_nop 0
	v_add_u32_e32 v82, -1, v3
	v_fma_f32 v85, -v82, v3, v2
	v_cmp_ge_f32_e64 s[4:5], 0, v85
	v_add_u32_e32 v85, 1, v3
	s_nop 0
	v_cndmask_b32_e64 v82, v3, v82, s[4:5]
	v_fma_f32 v3, -v85, v3, v2
	v_cmp_lt_f32_e64 s[4:5], 0, v3
	s_nop 1
	v_cndmask_b32_e64 v3, v82, v85, s[4:5]
	v_mul_f32_e32 v82, 0x37800000, v3
	v_cndmask_b32_e32 v3, v3, v82, vcc
	v_cmp_class_f32_e32 vcc, v2, v216
	s_nop 1
	v_cndmask_b32_e32 v2, v3, v2, vcc
	v_div_scale_f32 v3, s[0:1], v2, v2, s3
	v_rcp_f32_e32 v82, v3
	s_nop 0
	v_fma_f32 v85, -v3, v82, 1.0
	v_fmac_f32_e32 v82, v85, v82
	v_div_scale_f32 v85, vcc, s3, v2, s3
	v_mul_f32_e32 v97, v85, v82
	v_fma_f32 v98, -v3, v97, v85
	v_fmac_f32_e32 v97, v98, v82
	v_fma_f32 v3, -v3, v97, v85
	v_div_fmas_f32 v3, v3, v82, v97
	v_div_fixup_f32 v82, v3, v2, s3
	v_or_b32_e32 v2, s20, v83
	v_mul_f32_e32 v83, v84, v82
	v_mov_b32_e32 v84, v206
	v_or_b32_e32 v2, s31, v2
	v_mov_b32_e32 v3, v1
	v_lshlrev_b64 v[2:3], 11, v[2:3]
	v_lshl_add_u64 v[2:3], s[90:91], 0, v[2:3]
	v_lshl_add_u64 v[2:3], v[2:3], 0, s[26:27]
	v_lshl_add_u64 v[2:3], v[2:3], 0, v[0:1]
	v_mul_f32_e32 v81, v81, v82
	v_mul_f32_e32 v80, v80, v82
	s_nop 0
	v_mul_f32_e32 v83, v84, v83
	v_cvt_pk_bf16_f32 v83, v83, v1
	v_mov_b32_e32 v84, v207
	s_nop 0
	global_store_short v[2:3], v83, off
	v_mul_f32_e32 v83, v96, v82
	s_nop 0
	v_mul_f32_e32 v83, v84, v83
	v_cvt_pk_bf16_f32 v83, v83, v1
	global_store_short v[2:3], v83, off offset:64
	v_mov_b32_e32 v83, v208
	s_nop 0
	v_mul_f32_e32 v81, v83, v81
	v_cvt_pk_bf16_f32 v81, v81, v1
	global_store_short v[2:3], v81, off offset:128
	v_mov_b32_e32 v81, v209
	v_or_b32_e32 v83, 10, v228
	s_nop 0
	v_mul_f32_e32 v80, v80, v81
	v_cvt_pk_bf16_f32 v80, v80, v1
	global_store_short v[2:3], v80, off offset:192
	v_lshl_add_u32 v80, v83, 9, v11
	ds_read2_b32 v[2:3], v80 offset1:32
	s_waitcnt lgkmcnt(0)
	v_fma_f32 v84, v118, v148, -v2
	v_fma_f32 v85, v134, v148, -v3
	ds_read2_b32 v[2:3], v80 offset0:64 offset1:96
	v_mul_f32_e32 v82, v85, v85
	v_fmac_f32_e32 v82, v84, v84
	s_waitcnt lgkmcnt(0)
; __device__ __forceinline__ unsigned cvtpk(float lo, float hi) { unsigned r; asm volatile("v_cvt_pk_bf16_f32 %0, %1, %2" : "=v"(r) : "v"(lo), "v"(hi)); return r; }
; __device__ __forceinline__ float sx(float v, int mask, int lane) { return __int_as_float(__builtin_amdgcn_ds_bpermute((lane ^ mask) << 2, __float_as_int(v))); }
; __device__ __forceinline__ int crow(int r, int hi) { return (r & 3) + 8 * (r >> 2) + 4 * hi; }
;     __device__ __forceinline__ long qtok(int wid, int i) const { return (long)b * T + res + dil * (qs0 + 32 * wid + i); }
;     __device__ __forceinline__ long qtok(int wid, int i) const { return (long)b * T + 256 * qb + 32 * wid + i; }
;     __device__ __forceinline__ long qtok(int wid, int i) const { return (long)b * T + 128 * qb + 32 * (wid & 3) + i; }
; template <class Pol>
; __device__ __forceinline__ void attn_unit(const Pol& P, LAS unsigned char* lds, const Ptrs& X, bf16x8& pq0, bf16x8& pq1, bf16x8& pq2, bf16x8& pq3, bf16x8& pk_, bf16x8& pv_, bool have, const Pol& Pn, bool hasn) {
;     ...
;         if (wid < 4) {
; #pragma unroll
;             for (int r = 0; r < 16; ++r) { const int row = 32 * wid + crow(r, hi); float s = 0.f;
; #pragma unroll
;                 for (int d = 0; d < NB; ++d) { const float y = o[d][r] * rli[r] - XB[row * 128 + d * 32 + r32]; o[d][r] = y; s += y * y; }
;                 s += sx(s, 1, lane); s += sx(s, 2, lane); s += sx(s, 4, lane); s += sx(s, 8, lane); s += sx(s, 16, lane);
;                 const float rs = (1.0f - LAM_INIT) / sqrtf(s * (1.0f / 128.f) + SUBLN_EPS);
;                 const long tok = P.qtok(wid, crow(r, hi));
; #pragma unroll
;                 for (int d = 0; d < NB; ++d) X.att[tok * D + P.h * 128 + d * 32 + r32] = (bf16_t)(cvtpk(o[d][r] * rs * X.subln[d * 32 + r32], 0.f) & 0xffffu); }
;         }
	v_fma_f32 v81, v102, v148, -v2
	v_fmac_f32_e32 v82, v81, v81
	v_fma_f32 v80, v86, v148, -v3
	v_fmac_f32_e32 v82, v80, v80
	s_nop 1
	v_add_f32_dpp v2, v82, v82 quad_perm:[1,0,3,2] row_mask:0xf bank_mask:0xf
	s_nop 1
	v_add_f32_dpp v2, v2, v2 quad_perm:[2,3,0,1] row_mask:0xf bank_mask:0xf
	s_nop 1
	v_add_f32_dpp v2, v2, v2 row_half_mirror row_mask:0xf bank_mask:0xf
	s_nop 1
	v_add_f32_dpp v2, v2, v2 row_mirror row_mask:0xf bank_mask:0xf
	v_mov_b32_e32 v3, v2
	s_nop 1
	v_permlane16_swap_b32_e32 v3, v2
	v_add_f32_e32 v2, v2, v3
	v_fmamk_f32 v2, v2, 0x3c000000, v157
	v_cmp_gt_f32_e32 vcc, s2, v2
	v_mul_f32_e32 v3, 0x4f800000, v2
	s_nop 0
	v_cndmask_b32_e32 v2, v2, v3, vcc
	v_sqrt_f32_e32 v3, v2
	s_nop 0
	v_add_u32_e32 v82, -1, v3
	v_fma_f32 v86, -v82, v3, v2
	v_cmp_ge_f32_e64 s[4:5], 0, v86
	v_add_u32_e32 v86, 1, v3
	s_nop 0
	v_cndmask_b32_e64 v82, v3, v82, s[4:5]
	v_fma_f32 v3, -v86, v3, v2
	v_cmp_lt_f32_e64 s[4:5], 0, v3
	s_nop 1
	v_cndmask_b32_e64 v3, v82, v86, s[4:5]
	v_mul_f32_e32 v82, 0x37800000, v3
	v_cndmask_b32_e32 v3, v3, v82, vcc
	v_cmp_class_f32_e32 vcc, v2, v216
	s_nop 1
	v_cndmask_b32_e32 v2, v3, v2, vcc
	v_div_scale_f32 v3, s[0:1], v2, v2, s3
	v_rcp_f32_e32 v82, v3
	s_nop 0
	v_fma_f32 v86, -v3, v82, 1.0
	v_fmac_f32_e32 v82, v86, v82
	v_div_scale_f32 v86, vcc, s3, v2, s3
	v_mul_f32_e32 v96, v86, v82
	v_fma_f32 v97, -v3, v96, v86
	v_fmac_f32_e32 v96, v97, v82
	v_fma_f32 v3, -v3, v96, v86
	v_div_fmas_f32 v3, v3, v82, v96
	v_div_fixup_f32 v82, v3, v2, s3
	v_or_b32_e32 v2, s20, v83
	v_mul_f32_e32 v83, v84, v82
	v_mov_b32_e32 v84, v206
	v_or_b32_e32 v2, s31, v2
	v_mov_b32_e32 v3, v1
	v_lshlrev_b64 v[2:3], 11, v[2:3]
	v_lshl_add_u64 v[2:3], s[90:91], 0, v[2:3]
	v_lshl_add_u64 v[2:3], v[2:3], 0, s[26:27]
	v_lshl_add_u64 v[2:3], v[2:3], 0, v[0:1]
	v_mul_f32_e32 v81, v81, v82
	v_mul_f32_e32 v80, v80, v82
	s_nop 0
	v_mul_f32_e32 v83, v84, v83
	v_cvt_pk_bf16_f32 v83, v83, v1
	v_mov_b32_e32 v84, v207
	s_nop 0
	global_store_short v[2:3], v83, off
	v_mul_f32_e32 v83, v85, v82
	s_nop 0
	v_mul_f32_e32 v83, v84, v83
	v_cvt_pk_bf16_f32 v83, v83, v1
	global_store_short v[2:3], v83, off offset:64
	v_mov_b32_e32 v83, v208
	s_nop 0
	v_mul_f32_e32 v81, v83, v81
	v_cvt_pk_bf16_f32 v81, v81, v1
	global_store_short v[2:3], v81, off offset:128
	v_mov_b32_e32 v81, v209
	v_or_b32_e32 v83, 11, v228
	s_nop 0
	v_mul_f32_e32 v80, v80, v81
	v_cvt_pk_bf16_f32 v80, v80, v1
	global_store_short v[2:3], v80, off offset:192
	v_lshl_add_u32 v80, v83, 9, v11
	ds_read2_b32 v[2:3], v80 offset1:32
	s_waitcnt lgkmcnt(0)
	v_fma_f32 v84, v119, v147, -v2
	v_fma_f32 v85, v135, v147, -v3
	ds_read2_b32 v[2:3], v80 offset0:64 offset1:96
	v_mul_f32_e32 v82, v85, v85
	v_fmac_f32_e32 v82, v84, v84
	s_waitcnt lgkmcnt(0)
	v_fma_f32 v81, v103, v147, -v2
	v_fmac_f32_e32 v82, v81, v81
	v_fma_f32 v80, v87, v147, -v3
	v_fmac_f32_e32 v82, v80, v80
	s_nop 1
	v_add_f32_dpp v2, v82, v82 quad_perm:[1,0,3,2] row_mask:0xf bank_mask:0xf
	s_nop 1
	v_add_f32_dpp v2, v2, v2 quad_perm:[2,3,0,1] row_mask:0xf bank_mask:0xf
	s_nop 1
	v_add_f32_dpp v2, v2, v2 row_half_mirror row_mask:0xf bank_mask:0xf
	s_nop 1
	v_add_f32_dpp v2, v2, v2 row_mirror row_mask:0xf bank_mask:0xf
	v_mov_b32_e32 v3, v2
	s_nop 1
	v_permlane16_swap_b32_e32 v3, v2
	v_add_f32_e32 v2, v2, v3
	v_fmamk_f32 v2, v2, 0x3c000000, v157
	v_cmp_gt_f32_e32 vcc, s2, v2
	v_mul_f32_e32 v3, 0x4f800000, v2
	s_nop 0
	v_cndmask_b32_e32 v2, v2, v3, vcc
	v_sqrt_f32_e32 v3, v2
	s_nop 0
	v_add_u32_e32 v82, -1, v3
	v_fma_f32 v86, -v82, v3, v2
	v_cmp_ge_f32_e64 s[4:5], 0, v86
	v_add_u32_e32 v86, 1, v3
	s_nop 0
	v_cndmask_b32_e64 v82, v3, v82, s[4:5]
	v_fma_f32 v3, -v86, v3, v2
	v_cmp_lt_f32_e64 s[4:5], 0, v3
	s_nop 1
	v_cndmask_b32_e64 v3, v82, v86, s[4:5]
	v_mul_f32_e32 v82, 0x37800000, v3
	v_cndmask_b32_e32 v3, v3, v82, vcc
	v_cmp_class_f32_e32 vcc, v2, v216
	s_nop 1
	v_cndmask_b32_e32 v2, v3, v2, vcc
	v_div_scale_f32 v3, s[0:1], v2, v2, s3
	v_rcp_f32_e32 v82, v3
	s_nop 0
	v_fma_f32 v86, -v3, v82, 1.0
	v_fmac_f32_e32 v82, v86, v82
	v_div_scale_f32 v86, vcc, s3, v2, s3
	v_mul_f32_e32 v87, v86, v82
	v_fma_f32 v96, -v3, v87, v86
	v_fmac_f32_e32 v87, v96, v82
	v_fma_f32 v3, -v3, v87, v86
	v_div_fmas_f32 v3, v3, v82, v87
	v_div_fixup_f32 v82, v3, v2, s3
	v_or_b32_e32 v2, s20, v83
	v_mul_f32_e32 v83, v84, v82
	v_mov_b32_e32 v84, v206
	v_or_b32_e32 v2, s31, v2
	v_mov_b32_e32 v3, v1
	v_lshlrev_b64 v[2:3], 11, v[2:3]
	v_lshl_add_u64 v[2:3], s[90:91], 0, v[2:3]
	v_lshl_add_u64 v[2:3], v[2:3], 0, s[26:27]
	v_lshl_add_u64 v[2:3], v[2:3], 0, v[0:1]
	v_mul_f32_e32 v81, v81, v82
	v_mul_f32_e32 v80, v80, v82
	s_nop 0
	v_mul_f32_e32 v83, v84, v83
	v_cvt_pk_bf16_f32 v83, v83, v1
	v_mov_b32_e32 v84, v207
	s_nop 0
	global_store_short v[2:3], v83, off
	v_mul_f32_e32 v83, v85, v82
	s_nop 0
	v_mul_f32_e32 v83, v84, v83
	v_cvt_pk_bf16_f32 v83, v83, v1
	global_store_short v[2:3], v83, off offset:64
	v_mov_b32_e32 v83, v208
	s_nop 0
	v_mul_f32_e32 v81, v83, v81
	v_cvt_pk_bf16_f32 v81, v81, v1
	global_store_short v[2:3], v81, off offset:128
	v_mov_b32_e32 v81, v209
	v_or_b32_e32 v83, 16, v228
	s_nop 0
	v_mul_f32_e32 v80, v80, v81
	v_cvt_pk_bf16_f32 v80, v80, v1
	global_store_short v[2:3], v80, off offset:192
	v_lshl_add_u32 v80, v83, 9, v11
	ds_read2_b32 v[2:3], v80 offset1:32
	s_waitcnt lgkmcnt(0)
	v_fma_f32 v84, v120, v146, -v2
	v_fma_f32 v85, v136, v146, -v3
	ds_read2_b32 v[2:3], v80 offset0:64 offset1:96
	v_mul_f32_e32 v82, v85, v85
	v_fmac_f32_e32 v82, v84, v84
	s_waitcnt lgkmcnt(0)
; __device__ __forceinline__ unsigned cvtpk(float lo, float hi) { unsigned r; asm volatile("v_cvt_pk_bf16_f32 %0, %1, %2" : "=v"(r) : "v"(lo), "v"(hi)); return r; }
; __device__ __forceinline__ float sx(float v, int mask, int lane) { return __int_as_float(__builtin_amdgcn_ds_bpermute((lane ^ mask) << 2, __float_as_int(v))); }
; __device__ __forceinline__ int crow(int r, int hi) { return (r & 3) + 8 * (r >> 2) + 4 * hi; }
;     __device__ __forceinline__ long qtok(int wid, int i) const { return (long)b * T + res + dil * (qs0 + 32 * wid + i); }
;     __device__ __forceinline__ long qtok(int wid, int i) const { return (long)b * T + 256 * qb + 32 * wid + i; }
;     __device__ __forceinline__ long qtok(int wid, int i) const { return (long)b * T + 128 * qb + 32 * (wid & 3) + i; }
; template <class Pol>
; __device__ __forceinline__ void attn_unit(const Pol& P, LAS unsigned char* lds, const Ptrs& X, bf16x8& pq0, bf16x8& pq1, bf16x8& pq2, bf16x8& pq3, bf16x8& pk_, bf16x8& pv_, bool have, const Pol& Pn, bool hasn) {
;     ...
;         if (wid < 4) {
; #pragma unroll
;             for (int r = 0; r < 16; ++r) { const int row = 32 * wid + crow(r, hi); float s = 0.f;
; #pragma unroll
;                 for (int d = 0; d < NB; ++d) { const float y = o[d][r] * rli[r] - XB[row * 128 + d * 32 + r32]; o[d][r] = y; s += y * y; }
;                 s += sx(s, 1, lane); s += sx(s, 2, lane); s += sx(s, 4, lane); s += sx(s, 8, lane); s += sx(s, 16, lane);
;                 const float rs = (1.0f - LAM_INIT) / sqrtf(s * (1.0f / 128.f) + SUBLN_EPS);
;                 const long tok = P.qtok(wid, crow(r, hi));
; #pragma unroll
;                 for (int d = 0; d < NB; ++d) X.att[tok * D + P.h * 128 + d * 32 + r32] = (bf16_t)(cvtpk(o[d][r] * rs * X.subln[d * 32 + r32], 0.f) & 0xffffu); }
;         }
	v_fma_f32 v81, v104, v146, -v2
	v_fmac_f32_e32 v82, v81, v81
	v_fma_f32 v80, v88, v146, -v3
	v_fmac_f32_e32 v82, v80, v80
	s_nop 1
	v_add_f32_dpp v2, v82, v82 quad_perm:[1,0,3,2] row_mask:0xf bank_mask:0xf
	s_nop 1
	v_add_f32_dpp v2, v2, v2 quad_perm:[2,3,0,1] row_mask:0xf bank_mask:0xf
	s_nop 1
	v_add_f32_dpp v2, v2, v2 row_half_mirror row_mask:0xf bank_mask:0xf
	s_nop 1
	v_add_f32_dpp v2, v2, v2 row_mirror row_mask:0xf bank_mask:0xf
	v_mov_b32_e32 v3, v2
	s_nop 1
	v_permlane16_swap_b32_e32 v3, v2
	v_add_f32_e32 v2, v2, v3
	v_fmamk_f32 v2, v2, 0x3c000000, v157
	v_cmp_gt_f32_e32 vcc, s2, v2
	v_mul_f32_e32 v3, 0x4f800000, v2
	s_nop 0
	v_cndmask_b32_e32 v2, v2, v3, vcc
	v_sqrt_f32_e32 v3, v2
	s_nop 0
	v_add_u32_e32 v82, -1, v3
	v_fma_f32 v86, -v82, v3, v2
	v_cmp_ge_f32_e64 s[4:5], 0, v86
	v_add_u32_e32 v86, 1, v3
	s_nop 0
	v_cndmask_b32_e64 v82, v3, v82, s[4:5]
	v_fma_f32 v3, -v86, v3, v2
	v_cmp_lt_f32_e64 s[4:5], 0, v3
	s_nop 1
	v_cndmask_b32_e64 v3, v82, v86, s[4:5]
	v_mul_f32_e32 v82, 0x37800000, v3
	v_cndmask_b32_e32 v3, v3, v82, vcc
	v_cmp_class_f32_e32 vcc, v2, v216
	s_nop 1
	v_cndmask_b32_e32 v2, v3, v2, vcc
	v_div_scale_f32 v3, s[0:1], v2, v2, s3
	v_rcp_f32_e32 v82, v3
	s_nop 0
	v_fma_f32 v86, -v3, v82, 1.0
	v_fmac_f32_e32 v82, v86, v82
	v_div_scale_f32 v86, vcc, s3, v2, s3
	v_mul_f32_e32 v87, v86, v82
	v_fma_f32 v88, -v3, v87, v86
	v_fmac_f32_e32 v87, v88, v82
	v_fma_f32 v3, -v3, v87, v86
	v_div_fmas_f32 v3, v3, v82, v87
	v_div_fixup_f32 v82, v3, v2, s3
	v_or_b32_e32 v2, s20, v83
	v_mul_f32_e32 v83, v84, v82
	v_mov_b32_e32 v84, v206
	v_or_b32_e32 v2, s31, v2
	v_mov_b32_e32 v3, v1
	v_lshlrev_b64 v[2:3], 11, v[2:3]
	v_lshl_add_u64 v[2:3], s[90:91], 0, v[2:3]
	v_lshl_add_u64 v[2:3], v[2:3], 0, s[26:27]
	v_lshl_add_u64 v[2:3], v[2:3], 0, v[0:1]
	v_mul_f32_e32 v81, v81, v82
	v_mul_f32_e32 v80, v80, v82
	s_nop 0
	v_mul_f32_e32 v83, v84, v83
	v_cvt_pk_bf16_f32 v83, v83, v1
	v_mov_b32_e32 v84, v207
	s_nop 0
	global_store_short v[2:3], v83, off
	v_mul_f32_e32 v83, v85, v82
	s_nop 0
	v_mul_f32_e32 v83, v84, v83
	v_cvt_pk_bf16_f32 v83, v83, v1
	global_store_short v[2:3], v83, off offset:64
	v_mov_b32_e32 v83, v208
	s_nop 0
	v_mul_f32_e32 v81, v83, v81
	v_cvt_pk_bf16_f32 v81, v81, v1
	global_store_short v[2:3], v81, off offset:128
	v_mov_b32_e32 v81, v209
	v_or_b32_e32 v83, 17, v228
	s_nop 0
	v_mul_f32_e32 v80, v80, v81
	v_cvt_pk_bf16_f32 v80, v80, v1
	global_store_short v[2:3], v80, off offset:192
	v_lshl_add_u32 v80, v83, 9, v11
	ds_read2_b32 v[2:3], v80 offset1:32
	s_waitcnt lgkmcnt(0)
	v_fma_f32 v84, v121, v145, -v2
	v_fma_f32 v85, v137, v145, -v3
	ds_read2_b32 v[2:3], v80 offset0:64 offset1:96
	v_mul_f32_e32 v82, v85, v85
	v_fmac_f32_e32 v82, v84, v84
	s_waitcnt lgkmcnt(0)
	v_fma_f32 v81, v105, v145, -v2
	v_fmac_f32_e32 v82, v81, v81
	v_fma_f32 v80, v89, v145, -v3
	v_fmac_f32_e32 v82, v80, v80
	s_nop 1
	v_add_f32_dpp v2, v82, v82 quad_perm:[1,0,3,2] row_mask:0xf bank_mask:0xf
	s_nop 1
	v_add_f32_dpp v2, v2, v2 quad_perm:[2,3,0,1] row_mask:0xf bank_mask:0xf
	s_nop 1
	v_add_f32_dpp v2, v2, v2 row_half_mirror row_mask:0xf bank_mask:0xf
	s_nop 1
	v_add_f32_dpp v2, v2, v2 row_mirror row_mask:0xf bank_mask:0xf
	v_mov_b32_e32 v3, v2
	s_nop 1
	v_permlane16_swap_b32_e32 v3, v2
	v_add_f32_e32 v2, v2, v3
	v_fmamk_f32 v2, v2, 0x3c000000, v157
	v_cmp_gt_f32_e32 vcc, s2, v2
	v_mul_f32_e32 v3, 0x4f800000, v2
	s_nop 0
	v_cndmask_b32_e32 v2, v2, v3, vcc
	v_sqrt_f32_e32 v3, v2
	s_nop 0
	v_add_u32_e32 v82, -1, v3
	v_fma_f32 v86, -v82, v3, v2
	v_cmp_ge_f32_e64 s[4:5], 0, v86
	v_add_u32_e32 v86, 1, v3
	s_nop 0
	v_cndmask_b32_e64 v82, v3, v82, s[4:5]
	v_fma_f32 v3, -v86, v3, v2
	v_cmp_lt_f32_e64 s[4:5], 0, v3
	s_nop 1
	v_cndmask_b32_e64 v3, v82, v86, s[4:5]
	v_mul_f32_e32 v82, 0x37800000, v3
	v_cndmask_b32_e32 v3, v3, v82, vcc
	v_cmp_class_f32_e32 vcc, v2, v216
	s_nop 1
	v_cndmask_b32_e32 v2, v3, v2, vcc
	v_div_scale_f32 v3, s[0:1], v2, v2, s3
	v_rcp_f32_e32 v82, v3
	s_nop 0
	v_fma_f32 v86, -v3, v82, 1.0
	v_fmac_f32_e32 v82, v86, v82
	v_div_scale_f32 v86, vcc, s3, v2, s3
	v_mul_f32_e32 v87, v86, v82
	v_fma_f32 v88, -v3, v87, v86
	v_fmac_f32_e32 v87, v88, v82
	v_fma_f32 v3, -v3, v87, v86
	v_div_fmas_f32 v3, v3, v82, v87
	v_div_fixup_f32 v82, v3, v2, s3
	v_or_b32_e32 v2, s20, v83
	v_mul_f32_e32 v83, v84, v82
	v_mov_b32_e32 v84, v206
	v_or_b32_e32 v2, s31, v2
	v_mov_b32_e32 v3, v1
	v_lshlrev_b64 v[2:3], 11, v[2:3]
	v_lshl_add_u64 v[2:3], s[90:91], 0, v[2:3]
	v_lshl_add_u64 v[2:3], v[2:3], 0, s[26:27]
	v_lshl_add_u64 v[2:3], v[2:3], 0, v[0:1]
	v_mul_f32_e32 v81, v81, v82
	v_mul_f32_e32 v80, v80, v82
	s_nop 0
	v_mul_f32_e32 v83, v84, v83
	v_cvt_pk_bf16_f32 v83, v83, v1
	v_mov_b32_e32 v84, v207
	s_nop 0
	global_store_short v[2:3], v83, off
	v_mul_f32_e32 v83, v85, v82
	s_nop 0
	v_mul_f32_e32 v83, v84, v83
	v_cvt_pk_bf16_f32 v83, v83, v1
	global_store_short v[2:3], v83, off offset:64
	v_mov_b32_e32 v83, v208
	s_nop 0
	v_mul_f32_e32 v81, v83, v81
	v_cvt_pk_bf16_f32 v81, v81, v1
	global_store_short v[2:3], v81, off offset:128
	v_mov_b32_e32 v81, v209
	v_or_b32_e32 v83, 18, v228
	s_nop 0
	v_mul_f32_e32 v80, v80, v81
	v_cvt_pk_bf16_f32 v80, v80, v1
	global_store_short v[2:3], v80, off offset:192
	v_lshl_add_u32 v80, v83, 9, v11
	ds_read2_b32 v[2:3], v80 offset1:32
	s_waitcnt lgkmcnt(0)
	v_fma_f32 v84, v122, v144, -v2
	v_fma_f32 v85, v138, v144, -v3
	ds_read2_b32 v[2:3], v80 offset0:64 offset1:96
	v_mul_f32_e32 v82, v85, v85
	v_fmac_f32_e32 v82, v84, v84
	s_waitcnt lgkmcnt(0)
; __device__ __forceinline__ unsigned cvtpk(float lo, float hi) { unsigned r; asm volatile("v_cvt_pk_bf16_f32 %0, %1, %2" : "=v"(r) : "v"(lo), "v"(hi)); return r; }
; __device__ __forceinline__ float sx(float v, int mask, int lane) { return __int_as_float(__builtin_amdgcn_ds_bpermute((lane ^ mask) << 2, __float_as_int(v))); }
; __device__ __forceinline__ int crow(int r, int hi) { return (r & 3) + 8 * (r >> 2) + 4 * hi; }
;     __device__ __forceinline__ long qtok(int wid, int i) const { return (long)b * T + res + dil * (qs0 + 32 * wid + i); }
;     __device__ __forceinline__ long qtok(int wid, int i) const { return (long)b * T + 256 * qb + 32 * wid + i; }
;     __device__ __forceinline__ long qtok(int wid, int i) const { return (long)b * T + 128 * qb + 32 * (wid & 3) + i; }
; template <class Pol>
; __device__ __forceinline__ void attn_unit(const Pol& P, LAS unsigned char* lds, const Ptrs& X, bf16x8& pq0, bf16x8& pq1, bf16x8& pq2, bf16x8& pq3, bf16x8& pk_, bf16x8& pv_, bool have, const Pol& Pn, bool hasn) {
;     ...
;         if (wid < 4) {
; #pragma unroll
;             for (int r = 0; r < 16; ++r) { const int row = 32 * wid + crow(r, hi); float s = 0.f;
; #pragma unroll
;                 for (int d = 0; d < NB; ++d) { const float y = o[d][r] * rli[r] - XB[row * 128 + d * 32 + r32]; o[d][r] = y; s += y * y; }
;                 s += sx(s, 1, lane); s += sx(s, 2, lane); s += sx(s, 4, lane); s += sx(s, 8, lane); s += sx(s, 16, lane);
;                 const float rs = (1.0f - LAM_INIT) / sqrtf(s * (1.0f / 128.f) + SUBLN_EPS);
;                 const long tok = P.qtok(wid, crow(r, hi));
; #pragma unroll
;                 for (int d = 0; d < NB; ++d) X.att[tok * D + P.h * 128 + d * 32 + r32] = (bf16_t)(cvtpk(o[d][r] * rs * X.subln[d * 32 + r32], 0.f) & 0xffffu); }
;         }
	v_fma_f32 v81, v106, v144, -v2
	v_fmac_f32_e32 v82, v81, v81
	v_fma_f32 v80, v90, v144, -v3
	v_fmac_f32_e32 v82, v80, v80
	s_nop 1
	v_add_f32_dpp v2, v82, v82 quad_perm:[1,0,3,2] row_mask:0xf bank_mask:0xf
	s_nop 1
	v_add_f32_dpp v2, v2, v2 quad_perm:[2,3,0,1] row_mask:0xf bank_mask:0xf
	s_nop 1
	v_add_f32_dpp v2, v2, v2 row_half_mirror row_mask:0xf bank_mask:0xf
	s_nop 1
	v_add_f32_dpp v2, v2, v2 row_mirror row_mask:0xf bank_mask:0xf
	v_mov_b32_e32 v3, v2
	s_nop 1
	v_permlane16_swap_b32_e32 v3, v2
	v_add_f32_e32 v2, v2, v3
	v_fmamk_f32 v2, v2, 0x3c000000, v157
	v_cmp_gt_f32_e32 vcc, s2, v2
	v_mul_f32_e32 v3, 0x4f800000, v2
	s_nop 0
	v_cndmask_b32_e32 v2, v2, v3, vcc
	v_sqrt_f32_e32 v3, v2
	s_nop 0
	v_add_u32_e32 v82, -1, v3
	v_fma_f32 v86, -v82, v3, v2
	v_cmp_ge_f32_e64 s[4:5], 0, v86
	v_add_u32_e32 v86, 1, v3
	s_nop 0
	v_cndmask_b32_e64 v82, v3, v82, s[4:5]
	v_fma_f32 v3, -v86, v3, v2
	v_cmp_lt_f32_e64 s[4:5], 0, v3
	s_nop 1
	v_cndmask_b32_e64 v3, v82, v86, s[4:5]
	v_mul_f32_e32 v82, 0x37800000, v3
	v_cndmask_b32_e32 v3, v3, v82, vcc
	v_cmp_class_f32_e32 vcc, v2, v216
	s_nop 1
	v_cndmask_b32_e32 v2, v3, v2, vcc
	v_div_scale_f32 v3, s[0:1], v2, v2, s3
	v_rcp_f32_e32 v82, v3
	s_nop 0
	v_fma_f32 v86, -v3, v82, 1.0
	v_fmac_f32_e32 v82, v86, v82
	v_div_scale_f32 v86, vcc, s3, v2, s3
	v_mul_f32_e32 v87, v86, v82
	v_fma_f32 v88, -v3, v87, v86
	v_fmac_f32_e32 v87, v88, v82
	v_fma_f32 v3, -v3, v87, v86
	v_div_fmas_f32 v3, v3, v82, v87
	v_div_fixup_f32 v82, v3, v2, s3
	v_or_b32_e32 v2, s20, v83
	v_mul_f32_e32 v83, v84, v82
	v_mov_b32_e32 v84, v206
	v_or_b32_e32 v2, s31, v2
	v_mov_b32_e32 v3, v1
	v_lshlrev_b64 v[2:3], 11, v[2:3]
	v_lshl_add_u64 v[2:3], s[90:91], 0, v[2:3]
	v_lshl_add_u64 v[2:3], v[2:3], 0, s[26:27]
	v_lshl_add_u64 v[2:3], v[2:3], 0, v[0:1]
	v_mul_f32_e32 v81, v81, v82
	v_mul_f32_e32 v80, v80, v82
	s_nop 0
	v_mul_f32_e32 v83, v84, v83
	v_cvt_pk_bf16_f32 v83, v83, v1
	v_mov_b32_e32 v84, v207
	s_nop 0
	global_store_short v[2:3], v83, off
	v_mul_f32_e32 v83, v85, v82
	v_or_b32_e32 v82, 19, v228
	s_nop 0
	v_mul_f32_e32 v83, v84, v83
	v_cvt_pk_bf16_f32 v83, v83, v1
	global_store_short v[2:3], v83, off offset:64
	v_mov_b32_e32 v83, v208
	s_nop 0
	v_mul_f32_e32 v81, v83, v81
	v_cvt_pk_bf16_f32 v81, v81, v1
	global_store_short v[2:3], v81, off offset:128
	v_mov_b32_e32 v81, v209
	s_nop 0
	v_mul_f32_e32 v80, v80, v81
	v_cvt_pk_bf16_f32 v80, v80, v1
	global_store_short v[2:3], v80, off offset:192
	v_lshl_add_u32 v80, v82, 9, v11
	ds_read2_b32 v[2:3], v80 offset1:32
	s_waitcnt lgkmcnt(0)
	v_fma_f32 v83, v123, v15, -v2
	v_fma_f32 v84, v139, v15, -v3
	ds_read2_b32 v[2:3], v80 offset0:64 offset1:96
	v_mul_f32_e32 v81, v84, v84
	v_fmac_f32_e32 v81, v83, v83
	s_waitcnt lgkmcnt(0)
	v_fma_f32 v80, v107, v15, -v2
	v_fmac_f32_e32 v81, v80, v80
	v_fma_f32 v15, v91, v15, -v3
	v_fmac_f32_e32 v81, v15, v15
	s_nop 1
	v_add_f32_dpp v2, v81, v81 quad_perm:[1,0,3,2] row_mask:0xf bank_mask:0xf
	s_nop 1
	v_add_f32_dpp v2, v2, v2 quad_perm:[2,3,0,1] row_mask:0xf bank_mask:0xf
	s_nop 1
	v_add_f32_dpp v2, v2, v2 row_half_mirror row_mask:0xf bank_mask:0xf
	s_nop 1
	v_add_f32_dpp v2, v2, v2 row_mirror row_mask:0xf bank_mask:0xf
	v_mov_b32_e32 v3, v2
	s_nop 1
	v_permlane16_swap_b32_e32 v3, v2
	v_add_f32_e32 v2, v2, v3
	v_fmamk_f32 v2, v2, 0x3c000000, v157
	v_cmp_gt_f32_e32 vcc, s2, v2
	v_mul_f32_e32 v3, 0x4f800000, v2
	s_nop 0
	v_cndmask_b32_e32 v2, v2, v3, vcc
	v_sqrt_f32_e32 v3, v2
	s_nop 0
	v_add_u32_e32 v81, -1, v3
	v_fma_f32 v85, -v81, v3, v2
	v_cmp_ge_f32_e64 s[4:5], 0, v85
	v_add_u32_e32 v85, 1, v3
	s_nop 0
	v_cndmask_b32_e64 v81, v3, v81, s[4:5]
	v_fma_f32 v3, -v85, v3, v2
	v_cmp_lt_f32_e64 s[4:5], 0, v3
	s_nop 1
	v_cndmask_b32_e64 v3, v81, v85, s[4:5]
	v_mul_f32_e32 v81, 0x37800000, v3
	v_cndmask_b32_e32 v3, v3, v81, vcc
	v_cmp_class_f32_e32 vcc, v2, v216
	s_nop 1
	v_cndmask_b32_e32 v2, v3, v2, vcc
	v_div_scale_f32 v3, s[0:1], v2, v2, s3
	v_rcp_f32_e32 v81, v3
	s_nop 0
	v_fma_f32 v85, -v3, v81, 1.0
	v_fmac_f32_e32 v81, v85, v81
	v_div_scale_f32 v85, vcc, s3, v2, s3
	v_mul_f32_e32 v86, v85, v81
	v_fma_f32 v87, -v3, v86, v85
	v_fmac_f32_e32 v86, v87, v81
	v_fma_f32 v3, -v3, v86, v85
	v_div_fmas_f32 v3, v3, v81, v86
	v_div_fixup_f32 v81, v3, v2, s3
	v_or_b32_e32 v2, s20, v82
	v_mul_f32_e32 v82, v83, v81
	v_mov_b32_e32 v83, v206
	v_or_b32_e32 v2, s31, v2
	v_mov_b32_e32 v3, v1
	v_lshlrev_b64 v[2:3], 11, v[2:3]
	v_lshl_add_u64 v[2:3], s[90:91], 0, v[2:3]
	v_lshl_add_u64 v[2:3], v[2:3], 0, s[26:27]
	v_lshl_add_u64 v[2:3], v[2:3], 0, v[0:1]
	v_mul_f32_e32 v80, v80, v81
	v_mul_f32_e32 v15, v15, v81
	s_nop 0
	v_mul_f32_e32 v82, v83, v82
	v_cvt_pk_bf16_f32 v82, v82, v1
	v_mov_b32_e32 v83, v207
	s_nop 0
	global_store_short v[2:3], v82, off
	v_mul_f32_e32 v82, v84, v81
	v_or_b32_e32 v81, 24, v228
	s_nop 0
	v_mul_f32_e32 v82, v83, v82
	v_cvt_pk_bf16_f32 v82, v82, v1
	global_store_short v[2:3], v82, off offset:64
	v_mov_b32_e32 v82, v208
	s_nop 0
	v_mul_f32_e32 v80, v82, v80
	v_cvt_pk_bf16_f32 v80, v80, v1
	global_store_short v[2:3], v80, off offset:128
	v_mov_b32_e32 v80, v209
	s_nop 0
	v_mul_f32_e32 v15, v15, v80
	v_cvt_pk_bf16_f32 v15, v15, v1
	global_store_short v[2:3], v15, off offset:192
	v_lshl_add_u32 v15, v81, 9, v11
	ds_read2_b32 v[2:3], v15 offset1:32
	s_waitcnt lgkmcnt(0)
	v_fma_f32 v82, v124, v14, -v2
	v_fma_f32 v83, v140, v14, -v3
	ds_read2_b32 v[2:3], v15 offset0:64 offset1:96
	v_mul_f32_e32 v80, v83, v83
	v_fmac_f32_e32 v80, v82, v82
	s_waitcnt lgkmcnt(0)
; __device__ __forceinline__ unsigned cvtpk(float lo, float hi) { unsigned r; asm volatile("v_cvt_pk_bf16_f32 %0, %1, %2" : "=v"(r) : "v"(lo), "v"(hi)); return r; }
; __device__ __forceinline__ float sx(float v, int mask, int lane) { return __int_as_float(__builtin_amdgcn_ds_bpermute((lane ^ mask) << 2, __float_as_int(v))); }
; __device__ __forceinline__ int crow(int r, int hi) { return (r & 3) + 8 * (r >> 2) + 4 * hi; }
;     __device__ __forceinline__ long qtok(int wid, int i) const { return (long)b * T + res + dil * (qs0 + 32 * wid + i); }
;     __device__ __forceinline__ long qtok(int wid, int i) const { return (long)b * T + 256 * qb + 32 * wid + i; }
;     __device__ __forceinline__ long qtok(int wid, int i) const { return (long)b * T + 128 * qb + 32 * (wid & 3) + i; }
; template <class Pol>
; __device__ __forceinline__ void attn_unit(const Pol& P, LAS unsigned char* lds, const Ptrs& X, bf16x8& pq0, bf16x8& pq1, bf16x8& pq2, bf16x8& pq3, bf16x8& pk_, bf16x8& pv_, bool have, const Pol& Pn, bool hasn) {
;     ...
;         if (wid < 4) {
; #pragma unroll
;             for (int r = 0; r < 16; ++r) { const int row = 32 * wid + crow(r, hi); float s = 0.f;
; #pragma unroll
;                 for (int d = 0; d < NB; ++d) { const float y = o[d][r] * rli[r] - XB[row * 128 + d * 32 + r32]; o[d][r] = y; s += y * y; }
;                 s += sx(s, 1, lane); s += sx(s, 2, lane); s += sx(s, 4, lane); s += sx(s, 8, lane); s += sx(s, 16, lane);
;                 const float rs = (1.0f - LAM_INIT) / sqrtf(s * (1.0f / 128.f) + SUBLN_EPS);
;                 const long tok = P.qtok(wid, crow(r, hi));
; #pragma unroll
;                 for (int d = 0; d < NB; ++d) X.att[tok * D + P.h * 128 + d * 32 + r32] = (bf16_t)(cvtpk(o[d][r] * rs * X.subln[d * 32 + r32], 0.f) & 0xffffu); }
;         }
	v_fma_f32 v15, v108, v14, -v2
	v_fmac_f32_e32 v80, v15, v15
	v_fma_f32 v14, v92, v14, -v3
	v_fmac_f32_e32 v80, v14, v14
	s_nop 1
	v_add_f32_dpp v2, v80, v80 quad_perm:[1,0,3,2] row_mask:0xf bank_mask:0xf
	s_nop 1
	v_add_f32_dpp v2, v2, v2 quad_perm:[2,3,0,1] row_mask:0xf bank_mask:0xf
	s_nop 1
	v_add_f32_dpp v2, v2, v2 row_half_mirror row_mask:0xf bank_mask:0xf
	s_nop 1
	v_add_f32_dpp v2, v2, v2 row_mirror row_mask:0xf bank_mask:0xf
	v_mov_b32_e32 v3, v2
	s_nop 1
	v_permlane16_swap_b32_e32 v3, v2
	v_add_f32_e32 v2, v2, v3
	v_fmamk_f32 v2, v2, 0x3c000000, v157
	v_cmp_gt_f32_e32 vcc, s2, v2
	v_mul_f32_e32 v3, 0x4f800000, v2
	s_nop 0
	v_cndmask_b32_e32 v2, v2, v3, vcc
	v_sqrt_f32_e32 v3, v2
	s_nop 0
	v_add_u32_e32 v80, -1, v3
	v_fma_f32 v84, -v80, v3, v2
	v_cmp_ge_f32_e64 s[4:5], 0, v84
	v_add_u32_e32 v84, 1, v3
	s_nop 0
	v_cndmask_b32_e64 v80, v3, v80, s[4:5]
	v_fma_f32 v3, -v84, v3, v2
	v_cmp_lt_f32_e64 s[4:5], 0, v3
	s_nop 1
	v_cndmask_b32_e64 v3, v80, v84, s[4:5]
	v_mul_f32_e32 v80, 0x37800000, v3
	v_cndmask_b32_e32 v3, v3, v80, vcc
	v_cmp_class_f32_e32 vcc, v2, v216
	s_nop 1
	v_cndmask_b32_e32 v2, v3, v2, vcc
	v_div_scale_f32 v3, s[0:1], v2, v2, s3
	v_rcp_f32_e32 v80, v3
	s_nop 0
	v_fma_f32 v84, -v3, v80, 1.0
	v_fmac_f32_e32 v80, v84, v80
	v_div_scale_f32 v84, vcc, s3, v2, s3
	v_mul_f32_e32 v85, v84, v80
	v_fma_f32 v86, -v3, v85, v84
	v_fmac_f32_e32 v85, v86, v80
	v_fma_f32 v3, -v3, v85, v84
	v_div_fmas_f32 v3, v3, v80, v85
	v_div_fixup_f32 v80, v3, v2, s3
	v_or_b32_e32 v2, s20, v81
	v_mul_f32_e32 v81, v82, v80
	v_mov_b32_e32 v82, v206
	v_or_b32_e32 v2, s31, v2
	v_mov_b32_e32 v3, v1
	v_lshlrev_b64 v[2:3], 11, v[2:3]
	v_lshl_add_u64 v[2:3], s[90:91], 0, v[2:3]
	v_lshl_add_u64 v[2:3], v[2:3], 0, s[26:27]
	v_lshl_add_u64 v[2:3], v[2:3], 0, v[0:1]
	v_mul_f32_e32 v15, v15, v80
	v_mul_f32_e32 v14, v14, v80
	s_nop 0
	v_mul_f32_e32 v81, v82, v81
	v_cvt_pk_bf16_f32 v81, v81, v1
	v_mov_b32_e32 v82, v207
	s_nop 0
	global_store_short v[2:3], v81, off
	v_mul_f32_e32 v81, v83, v80
	v_or_b32_e32 v80, 25, v228
	s_nop 0
	v_mul_f32_e32 v81, v82, v81
	v_cvt_pk_bf16_f32 v81, v81, v1
	global_store_short v[2:3], v81, off offset:64
	v_mov_b32_e32 v81, v208
	s_nop 0
	v_mul_f32_e32 v15, v81, v15
	v_cvt_pk_bf16_f32 v15, v15, v1
	global_store_short v[2:3], v15, off offset:128
	v_mov_b32_e32 v15, v209
	s_nop 0
	v_mul_f32_e32 v14, v14, v15
	v_cvt_pk_bf16_f32 v14, v14, v1
	global_store_short v[2:3], v14, off offset:192
	v_lshl_add_u32 v14, v80, 9, v11
	ds_read2_b32 v[2:3], v14 offset1:32
	s_waitcnt lgkmcnt(0)
	v_fma_f32 v81, v125, v13, -v2
	v_fma_f32 v82, v141, v13, -v3
	ds_read2_b32 v[2:3], v14 offset0:64 offset1:96
	v_mul_f32_e32 v15, v82, v82
	v_fmac_f32_e32 v15, v81, v81
	s_waitcnt lgkmcnt(0)
	v_fma_f32 v14, v109, v13, -v2
	v_fmac_f32_e32 v15, v14, v14
	v_fma_f32 v13, v93, v13, -v3
	v_fmac_f32_e32 v15, v13, v13
	s_nop 1
	v_add_f32_dpp v2, v15, v15 quad_perm:[1,0,3,2] row_mask:0xf bank_mask:0xf
	s_nop 1
	v_add_f32_dpp v2, v2, v2 quad_perm:[2,3,0,1] row_mask:0xf bank_mask:0xf
	s_nop 1
	v_add_f32_dpp v2, v2, v2 row_half_mirror row_mask:0xf bank_mask:0xf
	s_nop 1
	v_add_f32_dpp v2, v2, v2 row_mirror row_mask:0xf bank_mask:0xf
	v_mov_b32_e32 v3, v2
	s_nop 1
	v_permlane16_swap_b32_e32 v3, v2
	v_add_f32_e32 v2, v2, v3
	v_fmamk_f32 v2, v2, 0x3c000000, v157
	v_cmp_gt_f32_e32 vcc, s2, v2
	v_mul_f32_e32 v3, 0x4f800000, v2
	s_nop 0
	v_cndmask_b32_e32 v2, v2, v3, vcc
	v_sqrt_f32_e32 v3, v2
	s_nop 0
	v_add_u32_e32 v15, -1, v3
	v_fma_f32 v83, -v15, v3, v2
	v_cmp_ge_f32_e64 s[4:5], 0, v83
	v_add_u32_e32 v83, 1, v3
	s_nop 0
	v_cndmask_b32_e64 v15, v3, v15, s[4:5]
	v_fma_f32 v3, -v83, v3, v2
	v_cmp_lt_f32_e64 s[4:5], 0, v3
	s_nop 1
	v_cndmask_b32_e64 v3, v15, v83, s[4:5]
	v_mul_f32_e32 v15, 0x37800000, v3
	v_cndmask_b32_e32 v3, v3, v15, vcc
	v_cmp_class_f32_e32 vcc, v2, v216
	s_nop 1
	v_cndmask_b32_e32 v2, v3, v2, vcc
	v_div_scale_f32 v3, s[0:1], v2, v2, s3
	v_rcp_f32_e32 v15, v3
	s_nop 0
	v_fma_f32 v83, -v3, v15, 1.0
	v_fmac_f32_e32 v15, v83, v15
	v_div_scale_f32 v83, vcc, s3, v2, s3
	v_mul_f32_e32 v84, v83, v15
	v_fma_f32 v85, -v3, v84, v83
	v_fmac_f32_e32 v84, v85, v15
	v_fma_f32 v3, -v3, v84, v83
	v_div_fmas_f32 v3, v3, v15, v84
	v_div_fixup_f32 v15, v3, v2, s3
	v_or_b32_e32 v2, s20, v80
	v_mul_f32_e32 v80, v81, v15
	v_mov_b32_e32 v81, v206
	v_or_b32_e32 v2, s31, v2
	v_mov_b32_e32 v3, v1
	v_lshlrev_b64 v[2:3], 11, v[2:3]
	v_lshl_add_u64 v[2:3], s[90:91], 0, v[2:3]
	v_lshl_add_u64 v[2:3], v[2:3], 0, s[26:27]
	v_lshl_add_u64 v[2:3], v[2:3], 0, v[0:1]
	v_mul_f32_e32 v14, v14, v15
	v_mul_f32_e32 v13, v13, v15
	s_nop 0
	v_mul_f32_e32 v80, v81, v80
	v_cvt_pk_bf16_f32 v80, v80, v1
	v_mov_b32_e32 v81, v207
	s_nop 0
	global_store_short v[2:3], v80, off
	v_mul_f32_e32 v80, v82, v15
	v_or_b32_e32 v15, 26, v228
	s_nop 0
	v_mul_f32_e32 v80, v81, v80
	v_cvt_pk_bf16_f32 v80, v80, v1
	global_store_short v[2:3], v80, off offset:64
	v_mov_b32_e32 v80, v208
	s_nop 0
	v_mul_f32_e32 v14, v80, v14
	v_cvt_pk_bf16_f32 v14, v14, v1
	global_store_short v[2:3], v14, off offset:128
	v_mov_b32_e32 v14, v209
	s_nop 0
	v_mul_f32_e32 v13, v13, v14
	v_cvt_pk_bf16_f32 v13, v13, v1
	global_store_short v[2:3], v13, off offset:192
	v_lshl_add_u32 v13, v15, 9, v11
	ds_read2_b32 v[2:3], v13 offset1:32
	s_waitcnt lgkmcnt(0)
; __device__ __forceinline__ unsigned cvtpk(float lo, float hi) { unsigned r; asm volatile("v_cvt_pk_bf16_f32 %0, %1, %2" : "=v"(r) : "v"(lo), "v"(hi)); return r; }
; __device__ __forceinline__ float sx(float v, int mask, int lane) { return __int_as_float(__builtin_amdgcn_ds_bpermute((lane ^ mask) << 2, __float_as_int(v))); }
; __device__ __forceinline__ int crow(int r, int hi) { return (r & 3) + 8 * (r >> 2) + 4 * hi; }
;     __device__ __forceinline__ long qtok(int wid, int i) const { return (long)b * T + res + dil * (qs0 + 32 * wid + i); }
;     __device__ __forceinline__ long qtok(int wid, int i) const { return (long)b * T + 256 * qb + 32 * wid + i; }
;     __device__ __forceinline__ long qtok(int wid, int i) const { return (long)b * T + 128 * qb + 32 * (wid & 3) + i; }
; template <class Pol>
; __device__ __forceinline__ void attn_unit(const Pol& P, LAS unsigned char* lds, const Ptrs& X, bf16x8& pq0, bf16x8& pq1, bf16x8& pq2, bf16x8& pq3, bf16x8& pk_, bf16x8& pv_, bool have, const Pol& Pn, bool hasn) {
;     ...
;         if (wid < 4) {
; #pragma unroll
;             for (int r = 0; r < 16; ++r) { const int row = 32 * wid + crow(r, hi); float s = 0.f;
; #pragma unroll
;                 for (int d = 0; d < NB; ++d) { const float y = o[d][r] * rli[r] - XB[row * 128 + d * 32 + r32]; o[d][r] = y; s += y * y; }
;                 s += sx(s, 1, lane); s += sx(s, 2, lane); s += sx(s, 4, lane); s += sx(s, 8, lane); s += sx(s, 16, lane);
;                 const float rs = (1.0f - LAM_INIT) / sqrtf(s * (1.0f / 128.f) + SUBLN_EPS);
;                 const long tok = P.qtok(wid, crow(r, hi));
; #pragma unroll
;                 for (int d = 0; d < NB; ++d) X.att[tok * D + P.h * 128 + d * 32 + r32] = (bf16_t)(cvtpk(o[d][r] * rs * X.subln[d * 32 + r32], 0.f) & 0xffffu); }
;         }
	v_fma_f32 v80, v126, v12, -v2
	v_fma_f32 v81, v142, v12, -v3
	ds_read2_b32 v[2:3], v13 offset0:64 offset1:96
	v_mul_f32_e32 v14, v81, v81
	v_fmac_f32_e32 v14, v80, v80
	s_waitcnt lgkmcnt(0)
	v_fma_f32 v13, v110, v12, -v2
	v_fmac_f32_e32 v14, v13, v13
	v_fma_f32 v12, v94, v12, -v3
	v_fmac_f32_e32 v14, v12, v12
	s_nop 1
	v_add_f32_dpp v2, v14, v14 quad_perm:[1,0,3,2] row_mask:0xf bank_mask:0xf
	s_nop 1
	v_add_f32_dpp v2, v2, v2 quad_perm:[2,3,0,1] row_mask:0xf bank_mask:0xf
	s_nop 1
	v_add_f32_dpp v2, v2, v2 row_half_mirror row_mask:0xf bank_mask:0xf
	s_nop 1
	v_add_f32_dpp v2, v2, v2 row_mirror row_mask:0xf bank_mask:0xf
	v_mov_b32_e32 v3, v2
	s_nop 1
	v_permlane16_swap_b32_e32 v3, v2
	v_add_f32_e32 v2, v2, v3
	v_fmamk_f32 v2, v2, 0x3c000000, v157
	v_cmp_gt_f32_e32 vcc, s2, v2
	v_mul_f32_e32 v3, 0x4f800000, v2
	s_nop 0
	v_cndmask_b32_e32 v2, v2, v3, vcc
	v_sqrt_f32_e32 v3, v2
	s_nop 0
	v_add_u32_e32 v14, -1, v3
	v_fma_f32 v82, -v14, v3, v2
	v_cmp_ge_f32_e64 s[4:5], 0, v82
	v_add_u32_e32 v82, 1, v3
	s_nop 0
	v_cndmask_b32_e64 v14, v3, v14, s[4:5]
	v_fma_f32 v3, -v82, v3, v2
	v_cmp_lt_f32_e64 s[4:5], 0, v3
	s_nop 1
	v_cndmask_b32_e64 v3, v14, v82, s[4:5]
	v_mul_f32_e32 v14, 0x37800000, v3
	v_cndmask_b32_e32 v3, v3, v14, vcc
	v_cmp_class_f32_e32 vcc, v2, v216
	s_nop 1
	v_cndmask_b32_e32 v2, v3, v2, vcc
	v_div_scale_f32 v3, s[0:1], v2, v2, s3
	v_rcp_f32_e32 v14, v3
	s_nop 0
	v_fma_f32 v82, -v3, v14, 1.0
	v_fmac_f32_e32 v14, v82, v14
	v_div_scale_f32 v82, vcc, s3, v2, s3
	v_mul_f32_e32 v83, v82, v14
	v_fma_f32 v84, -v3, v83, v82
	v_fmac_f32_e32 v83, v84, v14
	v_fma_f32 v3, -v3, v83, v82
	v_div_fmas_f32 v3, v3, v14, v83
	v_div_fixup_f32 v14, v3, v2, s3
	v_or_b32_e32 v2, s20, v15
	v_mul_f32_e32 v15, v80, v14
	v_mov_b32_e32 v80, v206
	v_or_b32_e32 v2, s31, v2
	v_mov_b32_e32 v3, v1
	v_lshlrev_b64 v[2:3], 11, v[2:3]
	v_lshl_add_u64 v[2:3], s[90:91], 0, v[2:3]
	v_lshl_add_u64 v[2:3], v[2:3], 0, s[26:27]
	v_lshl_add_u64 v[2:3], v[2:3], 0, v[0:1]
	v_mul_f32_e32 v13, v13, v14
	v_mul_f32_e32 v12, v12, v14
	s_nop 0
	v_mul_f32_e32 v15, v80, v15
	v_cvt_pk_bf16_f32 v15, v15, v1
	v_mov_b32_e32 v80, v207
	s_nop 0
	global_store_short v[2:3], v15, off
	v_mul_f32_e32 v15, v81, v14
	s_nop 0
	v_mul_f32_e32 v15, v80, v15
	v_cvt_pk_bf16_f32 v15, v15, v1
	global_store_short v[2:3], v15, off offset:64
	v_mov_b32_e32 v15, v208
	s_nop 0
	v_mul_f32_e32 v13, v15, v13
	v_cvt_pk_bf16_f32 v13, v13, v1
	global_store_short v[2:3], v13, off offset:128
	v_mov_b32_e32 v13, v209
	s_nop 0
	v_mul_f32_e32 v12, v12, v13
	v_or_b32_e32 v13, 27, v228
	v_lshl_add_u32 v11, v13, 9, v11
	v_cvt_pk_bf16_f32 v12, v12, v1
	global_store_short v[2:3], v12, off offset:192
	ds_read2_b32 v[2:3], v11 offset1:32
	s_waitcnt lgkmcnt(0)
	v_fma_f32 v14, v127, v5, -v2
	v_fma_f32 v12, v143, v5, -v3
	ds_read2_b32 v[2:3], v11 offset0:64 offset1:96
	v_mul_f32_e32 v15, v12, v12
	v_fmac_f32_e32 v15, v14, v14
	s_waitcnt lgkmcnt(0)
	v_fma_f32 v11, v111, v5, -v2
	v_fmac_f32_e32 v15, v11, v11
	v_fma_f32 v5, v95, v5, -v3
	v_fmac_f32_e32 v15, v5, v5
	s_nop 1
	v_add_f32_dpp v2, v15, v15 quad_perm:[1,0,3,2] row_mask:0xf bank_mask:0xf
	s_nop 1
	v_add_f32_dpp v2, v2, v2 quad_perm:[2,3,0,1] row_mask:0xf bank_mask:0xf
	s_nop 1
	v_add_f32_dpp v2, v2, v2 row_half_mirror row_mask:0xf bank_mask:0xf
	s_nop 1
	v_add_f32_dpp v2, v2, v2 row_mirror row_mask:0xf bank_mask:0xf
	v_mov_b32_e32 v3, v2
	s_nop 1
	v_permlane16_swap_b32_e32 v3, v2
	v_add_f32_e32 v2, v2, v3
	v_fmamk_f32 v2, v2, 0x3c000000, v157
	v_cmp_gt_f32_e32 vcc, s2, v2
	v_mul_f32_e32 v3, 0x4f800000, v2
	s_nop 0
	v_cndmask_b32_e32 v2, v2, v3, vcc
	v_sqrt_f32_e32 v3, v2
	s_nop 0
	v_add_u32_e32 v6, -1, v3
	v_fma_f32 v7, -v6, v3, v2
	v_cmp_ge_f32_e64 s[4:5], 0, v7
	v_add_u32_e32 v7, 1, v3
	s_nop 0
	v_cndmask_b32_e64 v6, v3, v6, s[4:5]
	v_fma_f32 v3, -v7, v3, v2
	v_cmp_lt_f32_e64 s[4:5], 0, v3
	s_nop 1
	v_cndmask_b32_e64 v3, v6, v7, s[4:5]
	v_mul_f32_e32 v6, 0x37800000, v3
	v_cndmask_b32_e32 v3, v3, v6, vcc
	v_cmp_class_f32_e32 vcc, v2, v216
	s_nop 1
	v_cndmask_b32_e32 v2, v3, v2, vcc
	v_div_scale_f32 v3, s[0:1], v2, v2, s3
	v_rcp_f32_e32 v6, v3
	s_nop 0
	v_fma_f32 v7, -v3, v6, 1.0
	v_fmac_f32_e32 v6, v7, v6
	v_div_scale_f32 v7, vcc, s3, v2, s3
	v_mul_f32_e32 v8, v7, v6
	v_fma_f32 v9, -v3, v8, v7
	v_fmac_f32_e32 v8, v9, v6
	v_fma_f32 v3, -v3, v8, v7
	v_div_fmas_f32 v3, v3, v6, v8
	v_mov_b32_e32 v8, v206
	v_div_fixup_f32 v6, v3, v2, s3
	v_or_b32_e32 v2, s20, v13
	v_or_b32_e32 v2, s31, v2
	v_mov_b32_e32 v3, v1
	v_lshlrev_b64 v[2:3], 11, v[2:3]
	v_mul_f32_e32 v7, v14, v6
	v_lshl_add_u64 v[2:3], s[90:91], 0, v[2:3]
	v_lshl_add_u64 v[2:3], v[2:3], 0, s[26:27]
	v_lshl_add_u64 v[2:3], v[2:3], 0, v[0:1]
	v_mul_f32_e32 v0, v12, v6
	s_nop 0
	v_mul_f32_e32 v7, v8, v7
	v_cvt_pk_bf16_f32 v7, v7, v1
	global_store_short v[2:3], v7, off
	v_mov_b32_e32 v7, v207
	s_nop 0
	v_mul_f32_e32 v0, v7, v0
	v_cvt_pk_bf16_f32 v0, v0, v1
	v_mov_b32_e32 v7, v208
	s_nop 0
	global_store_short v[2:3], v0, off offset:64
	v_mul_f32_e32 v0, v11, v6
	s_nop 0
	v_mul_f32_e32 v0, v7, v0
	v_cvt_pk_bf16_f32 v0, v0, v1
	v_mov_b32_e32 v4, v209
	s_nop 0
	global_store_short v[2:3], v0, off offset:128
	v_mul_f32_e32 v0, v5, v6
	s_nop 0
	v_mul_f32_e32 v0, v0, v4
	v_cvt_pk_bf16_f32 v0, v0, v1
	global_store_short v[2:3], v0, off offset:192
